# retention K tile staged by LDS-DMA with swizzled source addresses, K ds_writes removed
# speedup vs baseline: 1.0142x; 1.0082x over previous
.LBB0_864:
	s_lshl_b32 s4, s49, 6
	s_nop 1
	s_xor_b32 s49, s4, 64
	v_lshrrev_b32_e32 v2, 5, v170
	v_and_b32_e32 v3, 31, v170
	s_mulk_i32 s49, 0x220
	v_mul_u32_u24_e32 v1, 0x220, v2
	v_lshl_add_u32 v1, v3, 4, v1
	s_add_i32 s4, s49, 0x10800
	v_add_u32_e32 v1, s4, v1
	s_waitcnt vmcnt(3)
	ds_write_b128 v1, v[126:129]
	s_waitcnt vmcnt(2)
	ds_write_b128 v1, v[122:125] offset:8704
	s_add_i32 s48, s48, 1
	s_add_i32 s45, s45, 64
	s_cmp_eq_u32 s17, s48
	v_subrev_u32_e32 v196, 64, v196
	s_waitcnt vmcnt(1)
	ds_write_b128 v1, v[134:137] offset:17408
	s_waitcnt vmcnt(0)
	ds_write_b128 v1, v[130:133] offset:26112
	s_waitcnt lgkmcnt(0)
	s_barrier
	s_cbranch_scc1 .LBB0_870
.LBB0_865:
	s_and_b32 s49, s48, 1
	v_lshrrev_b32_e32 v4, 5, v170
	v_and_b32_e32 v5, 31, v170
	v_and_b32_e32 v6, 15, v4
	v_xor_b32_e32 v6, v5, v6
	v_lshlrev_b32_e32 v4, 14, v4
	v_lshl_or_b32 v6, v6, 4, v4
	v_lshl_or_b32 v4, v5, 4, v4
	s_lshl_b32 s4, s45, 14
	s_add_i32 s4, s4, 0x100000
	v_readlane_b32 s5, v254, 60
	s_lshl_b32 s5, s5, 10
	s_cmp_eq_u32 s49, 0
	s_cselect_b32 m0, 0x8400, 0
	s_add_i32 m0, m0, s5
	v_add_u32_e32 v0, s4, v6
	s_nop 0
	global_load_lds_dwordx4 v0, s[24:25]
	s_add_i32 m0, m0, 0x2000
	s_add_i32 s5, s4, 0x40000
	v_add_u32_e32 v1, s5, v6
	global_load_lds_dwordx4 v1, s[24:25]
	s_add_i32 m0, m0, 0x2000
	s_add_i32 s5, s4, 0x80000
	v_add_u32_e32 v2, s5, v6
	global_load_lds_dwordx4 v2, s[24:25]
	s_add_i32 m0, m0, 0x2000
	s_add_i32 s5, s4, 0xc0000
	v_add_u32_e32 v3, s5, v6
	global_load_lds_dwordx4 v3, s[24:25]
	v_add_u32_e32 v0, s4, v4
	s_add_i32 s5, s4, 0x40000
	v_add_u32_e32 v1, s5, v4
	s_add_i32 s5, s4, 0x80000
	v_add_u32_e32 v2, s5, v4
	s_add_i32 s5, s4, 0xc0000
	v_add_u32_e32 v3, s5, v4
	global_load_dwordx4 v[126:129], v0, s[26:27]
	global_load_dwordx4 v[122:125], v1, s[26:27]
	global_load_dwordx4 v[134:137], v2, s[26:27]
	global_load_dwordx4 v[130:133], v3, s[26:27]
	s_cmp_gt_i32 s45, s16
	s_cbranch_scc1 .LBB0_864
	s_mul_i32 s4, s49, 0x8400
	v_add_u32_e32 v8, s4, v195
	v_xor_b32_e32 v246, 64, v8
	v_xor_b32_e32 v247, 0x80, v8
	v_xor_b32_e32 v248, 0xc0, v8
	ds_read_b128 v[0:3], v8
	ds_read_b128 v[4:7], v8 offset:8192
	ds_read_b128 v[174:177], v8 offset:16384
	ds_read_b128 v[198:201], v8 offset:24576
	ds_read_b128 v[202:205], v246
	ds_read_b128 v[206:209], v246 offset:8192
	ds_read_b128 v[210:213], v246 offset:16384
	ds_read_b128 v[214:217], v246 offset:24576
	ds_read_b128 v[218:221], v247
	ds_read_b128 v[226:229], v247 offset:8192
	ds_read_b128 v[230:233], v247 offset:16384
	ds_read_b128 v[234:237], v247 offset:24576
	ds_read_b128 v[238:241], v248
	ds_read_b128 v[242:245], v248 offset:8192
	s_add_i32 s4, s45, 63
	s_cmp_le_u32 s4, s9
	s_waitcnt lgkmcnt(13)
	v_mfma_f32_16x16x32_bf16 v[150:153], v[0:3], v[102:105], 0
	ds_read_b128 v[0:3], v248 offset:16384
	s_waitcnt lgkmcnt(13)
	v_mfma_f32_16x16x32_bf16 v[146:149], v[4:7], v[102:105], 0
	ds_read_b128 v[4:7], v248 offset:24576
	s_waitcnt lgkmcnt(13)
	v_mfma_f32_16x16x32_bf16 v[142:145], v[174:177], v[102:105], 0
	ds_read_b128 v[174:177], v8 offset:256
	s_waitcnt lgkmcnt(13)
	v_mfma_f32_16x16x32_bf16 v[138:141], v[198:201], v[102:105], 0
	ds_read_b128 v[198:201], v8 offset:8448
	s_waitcnt lgkmcnt(13)
	v_mfma_f32_16x16x32_bf16 v[150:153], v[202:205], v[98:101], v[150:153]
	ds_read_b128 v[202:205], v8 offset:16640
	s_waitcnt lgkmcnt(13)
	v_mfma_f32_16x16x32_bf16 v[146:149], v[206:209], v[98:101], v[146:149]
	ds_read_b128 v[206:209], v8 offset:24832
	s_waitcnt lgkmcnt(13)
	v_mfma_f32_16x16x32_bf16 v[142:145], v[210:213], v[98:101], v[142:145]
	ds_read_b128 v[210:213], v246 offset:256
	s_waitcnt lgkmcnt(13)
	v_mfma_f32_16x16x32_bf16 v[138:141], v[214:217], v[98:101], v[138:141]
	ds_read_b128 v[214:217], v246 offset:8448
	s_waitcnt lgkmcnt(13)
	v_mfma_f32_16x16x32_bf16 v[150:153], v[218:221], v[94:97], v[150:153]
	ds_read_b128 v[218:221], v246 offset:16640
	s_waitcnt lgkmcnt(13)
	v_mfma_f32_16x16x32_bf16 v[146:149], v[226:229], v[94:97], v[146:149]
	ds_read_b128 v[226:229], v246 offset:24832
	s_waitcnt lgkmcnt(13)
	v_mfma_f32_16x16x32_bf16 v[142:145], v[230:233], v[94:97], v[142:145]
	ds_read_b128 v[230:233], v247 offset:256
	s_waitcnt lgkmcnt(13)
	v_mfma_f32_16x16x32_bf16 v[138:141], v[234:237], v[94:97], v[138:141]
	ds_read_b128 v[234:237], v247 offset:8448
	s_waitcnt lgkmcnt(13)
	v_mfma_f32_16x16x32_bf16 v[150:153], v[238:241], v[90:93], v[150:153]
	ds_read_b128 v[238:241], v247 offset:16640
	s_waitcnt lgkmcnt(13)
	v_mfma_f32_16x16x32_bf16 v[146:149], v[242:245], v[90:93], v[146:149]
	ds_read_b128 v[242:245], v247 offset:24832
	s_waitcnt lgkmcnt(13)
	v_mfma_f32_16x16x32_bf16 v[142:145], v[0:3], v[90:93], v[142:145]
	ds_read_b128 v[0:3], v248 offset:256
	s_waitcnt lgkmcnt(13)
	v_mfma_f32_16x16x32_bf16 v[138:141], v[4:7], v[90:93], v[138:141]
	ds_read_b128 v[4:7], v248 offset:8448
	s_waitcnt lgkmcnt(13)
	v_mfma_f32_16x16x32_bf16 v[150:153], v[174:177], v[86:89], v[150:153]
	ds_read_b128 v[174:177], v248 offset:16640
	s_waitcnt lgkmcnt(13)
	v_mfma_f32_16x16x32_bf16 v[146:149], v[198:201], v[86:89], v[146:149]
	ds_read_b128 v[198:201], v248 offset:24832
	s_waitcnt lgkmcnt(13)
	v_mfma_f32_16x16x32_bf16 v[142:145], v[202:205], v[86:89], v[142:145]
	s_waitcnt lgkmcnt(12)
	v_mfma_f32_16x16x32_bf16 v[138:141], v[206:209], v[86:89], v[138:141]
	s_waitcnt lgkmcnt(11)
	v_mfma_f32_16x16x32_bf16 v[150:153], v[210:213], v[82:85], v[150:153]
	s_waitcnt lgkmcnt(10)
	v_mfma_f32_16x16x32_bf16 v[146:149], v[214:217], v[82:85], v[146:149]
	s_waitcnt lgkmcnt(9)
	v_mfma_f32_16x16x32_bf16 v[142:145], v[218:221], v[82:85], v[142:145]
	s_waitcnt lgkmcnt(8)
	v_mfma_f32_16x16x32_bf16 v[138:141], v[226:229], v[82:85], v[138:141]
	s_waitcnt lgkmcnt(7)
	v_mfma_f32_16x16x32_bf16 v[150:153], v[230:233], v[78:81], v[150:153]
	s_waitcnt lgkmcnt(6)
	v_mfma_f32_16x16x32_bf16 v[146:149], v[234:237], v[78:81], v[146:149]
	s_waitcnt lgkmcnt(5)
	v_mfma_f32_16x16x32_bf16 v[142:145], v[238:241], v[78:81], v[142:145]
	s_waitcnt lgkmcnt(4)
	v_mfma_f32_16x16x32_bf16 v[138:141], v[242:245], v[78:81], v[138:141]
	s_waitcnt lgkmcnt(3)
	v_mfma_f32_16x16x32_bf16 v[150:153], v[0:3], v[74:77], v[150:153]
	s_waitcnt lgkmcnt(2)
	v_mfma_f32_16x16x32_bf16 v[146:149], v[4:7], v[74:77], v[146:149]
	s_waitcnt lgkmcnt(1)
	v_mfma_f32_16x16x32_bf16 v[142:145], v[174:177], v[74:77], v[142:145]
	s_waitcnt lgkmcnt(0)
	v_mfma_f32_16x16x32_bf16 v[138:141], v[198:201], v[74:77], v[138:141]
	s_mov_b64 s[4:5], -1
	s_cbranch_scc0 .LBB0_868
	v_cvt_f32_i32_e32 v0, v196
	s_mov_b64 s[4:5], 0
	v_mul_f32_e32 v0, v178, v0
	v_exp_f32_e32 v8, v0
	s_nop 0
	v_mul_f32_e32 v0, s40, v8
	v_pk_mul_f32 v[2:3], s[40:41], v[0:1] op_sel_hi:[1,0]
	v_pk_mul_f32 v[0:1], s[42:43], v[0:1] op_sel_hi:[1,0]
	v_pk_mul_f32 v[2:3], v[2:3], v[150:151]
	v_pk_mul_f32 v[4:5], v[0:1], v[152:153]
	v_cvt_pk_bf16_f32 v0, v2, v3
	v_mul_f32_e32 v2, s44, v8
	v_cvt_pk_bf16_f32 v1, v4, v5
	v_pk_mul_f32 v[4:5], s[40:41], v[2:3] op_sel_hi:[1,0]
	v_pk_mul_f32 v[2:3], s[42:43], v[2:3] op_sel_hi:[1,0]
	v_pk_mul_f32 v[4:5], v[4:5], v[146:147]
	v_pk_mul_f32 v[6:7], v[2:3], v[148:149]
	v_cvt_pk_bf16_f32 v2, v4, v5
	v_mul_f32_e32 v4, s37, v8
	v_cvt_pk_bf16_f32 v3, v6, v7
	v_pk_mul_f32 v[6:7], s[40:41], v[4:5] op_sel_hi:[1,0]
	v_pk_mul_f32 v[4:5], s[42:43], v[4:5] op_sel_hi:[1,0]
	v_pk_mul_f32 v[6:7], v[6:7], v[142:143]
	v_pk_mul_f32 v[154:155], v[4:5], v[144:145]
	v_cvt_pk_bf16_f32 v4, v6, v7
	v_mul_f32_e32 v6, s36, v8
	v_cvt_pk_bf16_f32 v5, v154, v155
	v_pk_mul_f32 v[154:155], s[40:41], v[6:7] op_sel_hi:[1,0]
	v_pk_mul_f32 v[6:7], s[42:43], v[6:7] op_sel_hi:[1,0]
	v_pk_mul_f32 v[174:175], v[154:155], v[138:139]
	v_pk_mul_f32 v[176:177], v[6:7], v[140:141]
